# attention items moved from phase s1 into phase s3 (waves 0-3: attention then pass 2; waves 4-7: pass 2 then attention)
# baseline (speedup 1.0000x reference)
.LBB0_165:
	s_and_b64 vcc, exec, s[2:3]
	s_cbranch_vccz .LBB0_174
	s_mov_b32 s101, 1
	s_cmp_lg_u32 s34, 0x100
	s_cbranch_scc1 .Ls3_pass2
	s_mov_b32 s101, 0
	v_readfirstlane_b32 s100, v206
	s_nop 3
	s_lshr_b32 s100, s100, 8
	s_cmp_eq_u32 s100, 0
	s_cbranch_scc1 .Ls3_attn
.Ls3_pass2:
	v_mov_b32_e32 v0, v206
	s_lshl_b32 s3, s20, 3
	v_ashrrev_i32_e32 v0, 6, v0
	v_add_u32_e32 v46, s3, v0
	s_movk_i32 s2, 0x2000
	v_cmp_gt_i32_e32 vcc, s2, v46
	s_and_saveexec_b64 s[36:37], vcc
	s_cbranch_execz .LBB0_173
	s_lshl_b32 s4, s24, 8
	s_ashr_i32 s5, s4, 31
	s_lshl_b64 s[4:5], s[4:5], 2
	s_add_u32 s38, s56, s4
	s_addc_u32 s39, s57, s5
	v_add_u32_e32 v0, s3, v0
	s_add_u32 s40, s54, s4
	v_add_u32_e32 v0, 0xfffff000, v0
	s_addc_u32 s41, s55, s5
	s_lshl_b32 s2, s72, 3
	v_lshlrev_b32_e32 v47, 9, v0
	s_lshl_b32 s3, s72, 12
	v_lshlrev_b32_e32 v48, 4, v0
	s_lshl_b32 s6, s72, 7
	v_lshlrev_b32_e32 v49, 2, v0
	s_lshl_b32 s7, s72, 5
	s_mov_b64 s[84:85], 0
	s_branch .LBB0_169

.LBB0_173:
	s_or_b64 exec, exec, s[36:37]
	s_bitcmp1_b32 s101, 0
	s_cbranch_scc1 .LBB0_174
	s_or_b32 s101, s101, 2
	s_branch .Ls3_attn

.LBB0_180:
	s_andn2_b64 vcc, exec, s[2:3]
	s_cbranch_vccnz .LBB0_305
	s_cmpk_gt_i32 s20, 0x4ff
	s_cbranch_scc1 .LBB0_305
	s_ashr_i32 s25, s24, 31
	s_lshl_b64 s[2:3], s[24:25], 13
	s_add_u32 s82, s48, s2
	s_addc_u32 s83, s49, s3
	s_lshl_b32 s8, s24, 7
	s_cmp_gt_i32 s70, 7
	s_cselect_b64 s[30:31], -1, 0
	s_cmp_lg_u32 s34, 0x100
	s_cbranch_scc1 .Ls1_keep
	s_add_i32 s20, s20, s72
.Ls1_keep:
	s_lshl_b32 s9, s20, 3
	s_lshl_b32 s10, s72, 3
	s_branch .LBB0_190

.LBB0_188:
	s_or_b64 exec, exec, s[4:5]
	v_lshlrev_b32_e32 v176, 1, v125
	v_lshl_add_u64 v[32:33], v[126:127], 0, v[176:177]
	global_load_dwordx2 v[46:47], v[32:33], off offset:1024
	global_load_dwordx2 v[44:45], v[32:33], off offset:1040
	global_load_dwordx2 v[42:43], v[32:33], off offset:1056
	global_load_dwordx2 v[40:41], v[32:33], off offset:1072
	global_load_dwordx2 v[38:39], v[32:33], off offset:1088
	global_load_dwordx2 v[36:37], v[32:33], off offset:1104
	global_load_dwordx2 v[34:35], v[32:33], off offset:1120
	s_nop 0
	global_load_dwordx2 v[32:33], v[32:33], off offset:1136
	v_readlane_b32 s2, v254, 13
	v_readlane_b32 s3, v254, 14
	v_mov_b32_e32 v125, v177
	s_waitcnt vmcnt(7)
	v_lshlrev_b32_e32 v50, 16, v46
	v_and_b32_e32 v51, 0xffff0000, v46
	v_mul_f32_e32 v46, 0xbfb8aa3b, v50
	v_exp_f32_e32 v46, v46
	v_mov_b64_e32 v[48:49], s[2:3]
	v_mad_i64_i32 v[48:49], s[2:3], v136, s67, v[48:49]
	v_add_f32_e32 v46, 1.0, v46
	v_rcp_f32_e32 v52, v46
	v_mul_f32_e32 v46, 0xbfb8aa3b, v51
	v_exp_f32_e32 v46, v46
	v_lshl_add_u64 v[48:49], v[48:49], 0, v[124:125]
	v_add_f32_e32 v46, 1.0, v46
	v_rcp_f32_e32 v53, v46
	s_nop 0
	v_pk_mul_f32 v[50:51], v[52:53], v[50:51]
	s_nop 0
	v_pk_mul_f32 v[16:17], v[16:17], v[50:51]
	s_nop 0
	v_cvt_pk_bf16_f32 v46, v16, v17
	v_lshlrev_b32_e32 v16, 16, v47
	v_and_b32_e32 v17, 0xffff0000, v47
	v_mul_f32_e32 v47, 0xbfb8aa3b, v16
	v_exp_f32_e32 v47, v47
	s_nop 0
	v_add_f32_e32 v47, 1.0, v47
	v_rcp_f32_e32 v50, v47
	v_mul_f32_e32 v47, 0xbfb8aa3b, v17
	v_exp_f32_e32 v47, v47
	s_nop 0
	v_add_f32_e32 v47, 1.0, v47
	v_rcp_f32_e32 v51, v47
	s_nop 0
	v_pk_mul_f32 v[16:17], v[50:51], v[16:17]
	s_nop 0
	v_pk_mul_f32 v[16:17], v[18:19], v[16:17]
	s_waitcnt vmcnt(6)
	v_lshlrev_b32_e32 v18, 16, v44
	v_and_b32_e32 v19, 0xffff0000, v44
	v_mul_f32_e32 v44, 0xbfb8aa3b, v18
	v_exp_f32_e32 v44, v44
	v_cvt_pk_bf16_f32 v47, v16, v17
	v_lshl_add_u64 v[16:17], v[48:49], 0, v[176:177]
	global_store_dwordx2 v[16:17], v[46:47], off
	v_add_f32_e32 v44, 1.0, v44
	v_rcp_f32_e32 v46, v44
	v_mul_f32_e32 v44, 0xbfb8aa3b, v19
	v_exp_f32_e32 v44, v44
	s_nop 0
	v_add_f32_e32 v44, 1.0, v44
	v_rcp_f32_e32 v47, v44
	s_nop 0
	v_pk_mul_f32 v[18:19], v[46:47], v[18:19]
	s_nop 0
	v_pk_mul_f32 v[18:19], v[20:21], v[18:19]
	v_lshlrev_b32_e32 v20, 16, v45
	v_cvt_pk_bf16_f32 v18, v18, v19
	v_mul_f32_e32 v19, 0xbfb8aa3b, v20
	v_exp_f32_e32 v19, v19
	v_and_b32_e32 v21, 0xffff0000, v45
	v_add_f32_e32 v19, 1.0, v19
	v_rcp_f32_e32 v44, v19
	v_mul_f32_e32 v19, 0xbfb8aa3b, v21
	v_exp_f32_e32 v19, v19
	s_nop 0
	v_add_f32_e32 v19, 1.0, v19
	v_rcp_f32_e32 v45, v19
	s_nop 0
	v_pk_mul_f32 v[20:21], v[44:45], v[20:21]
	s_nop 0
	v_pk_mul_f32 v[20:21], v[22:23], v[20:21]
	s_nop 0
	v_cvt_pk_bf16_f32 v19, v20, v21
	global_store_dwordx2 v[16:17], v[18:19], off offset:16
	s_waitcnt vmcnt(7)
	v_lshlrev_b32_e32 v18, 16, v42
	v_and_b32_e32 v19, 0xffff0000, v42
	v_mul_f32_e32 v20, 0xbfb8aa3b, v18
	v_mul_f32_e32 v21, 0xbfb8aa3b, v19
	v_exp_f32_e32 v20, v20
	v_exp_f32_e32 v21, v21
	v_add_f32_e32 v20, 1.0, v20
	v_add_f32_e32 v21, 1.0, v21
	v_rcp_f32_e32 v20, v20
	v_rcp_f32_e32 v21, v21
	s_nop 0
	v_pk_mul_f32 v[18:19], v[20:21], v[18:19]
	s_nop 0
	v_pk_mul_f32 v[18:19], v[24:25], v[18:19]
	v_lshlrev_b32_e32 v20, 16, v43
	v_cvt_pk_bf16_f32 v18, v18, v19
	v_mul_f32_e32 v19, 0xbfb8aa3b, v20
	v_exp_f32_e32 v19, v19
	v_and_b32_e32 v21, 0xffff0000, v43
	v_add_f32_e32 v19, 1.0, v19
	v_rcp_f32_e32 v22, v19
	v_mul_f32_e32 v19, 0xbfb8aa3b, v21
	v_exp_f32_e32 v19, v19
	s_nop 0
	v_add_f32_e32 v19, 1.0, v19
	v_rcp_f32_e32 v23, v19
	s_nop 0
	v_pk_mul_f32 v[20:21], v[22:23], v[20:21]
	s_nop 0
	v_pk_mul_f32 v[20:21], v[26:27], v[20:21]
	s_nop 0
	v_cvt_pk_bf16_f32 v19, v20, v21
	global_store_dwordx2 v[16:17], v[18:19], off offset:32
	s_waitcnt vmcnt(7)
	v_lshlrev_b32_e32 v18, 16, v40
	v_and_b32_e32 v19, 0xffff0000, v40
	v_mul_f32_e32 v20, 0xbfb8aa3b, v18
	v_mul_f32_e32 v21, 0xbfb8aa3b, v19
	v_exp_f32_e32 v20, v20
	v_exp_f32_e32 v21, v21
	v_add_f32_e32 v20, 1.0, v20
	v_add_f32_e32 v21, 1.0, v21
	v_rcp_f32_e32 v20, v20
	v_rcp_f32_e32 v21, v21
	s_nop 0
	v_pk_mul_f32 v[18:19], v[20:21], v[18:19]
	s_nop 0
	v_pk_mul_f32 v[18:19], v[28:29], v[18:19]
	v_lshlrev_b32_e32 v20, 16, v41
	v_cvt_pk_bf16_f32 v18, v18, v19
	v_mul_f32_e32 v19, 0xbfb8aa3b, v20
	v_exp_f32_e32 v19, v19
	v_and_b32_e32 v21, 0xffff0000, v41
	v_add_f32_e32 v19, 1.0, v19
	v_rcp_f32_e32 v22, v19
	v_mul_f32_e32 v19, 0xbfb8aa3b, v21
	v_exp_f32_e32 v19, v19
	s_nop 0
	v_add_f32_e32 v19, 1.0, v19
	v_rcp_f32_e32 v23, v19
	s_nop 0
	v_pk_mul_f32 v[20:21], v[22:23], v[20:21]
	s_nop 0
	v_pk_mul_f32 v[20:21], v[30:31], v[20:21]
	s_nop 0
	v_cvt_pk_bf16_f32 v19, v20, v21
	global_store_dwordx2 v[16:17], v[18:19], off offset:48
	s_waitcnt vmcnt(7)
	v_lshlrev_b32_e32 v18, 16, v38
	v_and_b32_e32 v19, 0xffff0000, v38
	v_mul_f32_e32 v20, 0xbfb8aa3b, v18
	v_mul_f32_e32 v21, 0xbfb8aa3b, v19
	v_exp_f32_e32 v20, v20
	v_exp_f32_e32 v21, v21
	v_add_f32_e32 v20, 1.0, v20
	v_add_f32_e32 v21, 1.0, v21
	v_rcp_f32_e32 v20, v20
	v_rcp_f32_e32 v21, v21
	s_nop 0
	v_pk_mul_f32 v[18:19], v[20:21], v[18:19]
	s_nop 0
	v_pk_mul_f32 v[0:1], v[0:1], v[18:19]
	v_lshlrev_b32_e32 v18, 16, v39
	v_cvt_pk_bf16_f32 v0, v0, v1
	v_mul_f32_e32 v1, 0xbfb8aa3b, v18
	v_exp_f32_e32 v1, v1
	v_and_b32_e32 v19, 0xffff0000, v39
	v_add_f32_e32 v1, 1.0, v1
	v_rcp_f32_e32 v20, v1
	v_mul_f32_e32 v1, 0xbfb8aa3b, v19
	v_exp_f32_e32 v1, v1
	s_nop 0
	v_add_f32_e32 v1, 1.0, v1
	v_rcp_f32_e32 v21, v1
	s_nop 0
	v_pk_mul_f32 v[18:19], v[20:21], v[18:19]
	s_nop 0
	v_pk_mul_f32 v[2:3], v[2:3], v[18:19]
	s_nop 0
	v_cvt_pk_bf16_f32 v1, v2, v3
	global_store_dwordx2 v[16:17], v[0:1], off offset:64
	s_waitcnt vmcnt(7)
	v_lshlrev_b32_e32 v0, 16, v36
	v_and_b32_e32 v1, 0xffff0000, v36
	v_mul_f32_e32 v2, 0xbfb8aa3b, v0
	v_mul_f32_e32 v3, 0xbfb8aa3b, v1
	v_exp_f32_e32 v2, v2
	v_exp_f32_e32 v3, v3
	v_add_f32_e32 v2, 1.0, v2
	v_add_f32_e32 v3, 1.0, v3
	v_rcp_f32_e32 v2, v2
	v_rcp_f32_e32 v3, v3
	s_nop 0
	v_pk_mul_f32 v[0:1], v[2:3], v[0:1]
	s_nop 0
	v_pk_mul_f32 v[0:1], v[4:5], v[0:1]
	v_lshlrev_b32_e32 v2, 16, v37
	v_cvt_pk_bf16_f32 v0, v0, v1
	v_mul_f32_e32 v1, 0xbfb8aa3b, v2
	v_exp_f32_e32 v1, v1
	v_and_b32_e32 v3, 0xffff0000, v37
	v_add_f32_e32 v1, 1.0, v1
	v_rcp_f32_e32 v4, v1
	v_mul_f32_e32 v1, 0xbfb8aa3b, v3
	v_exp_f32_e32 v1, v1
	s_nop 0
	v_add_f32_e32 v1, 1.0, v1
	v_rcp_f32_e32 v5, v1
	s_nop 0
	v_pk_mul_f32 v[2:3], v[4:5], v[2:3]
	s_nop 0
	v_pk_mul_f32 v[2:3], v[6:7], v[2:3]
	s_nop 0
	v_cvt_pk_bf16_f32 v1, v2, v3
	global_store_dwordx2 v[16:17], v[0:1], off offset:80
	s_waitcnt vmcnt(7)
	v_lshlrev_b32_e32 v0, 16, v34
	v_and_b32_e32 v1, 0xffff0000, v34
	v_mul_f32_e32 v2, 0xbfb8aa3b, v0
	v_mul_f32_e32 v3, 0xbfb8aa3b, v1
	v_exp_f32_e32 v2, v2
	v_exp_f32_e32 v3, v3
	v_add_f32_e32 v2, 1.0, v2
	v_add_f32_e32 v3, 1.0, v3
	v_rcp_f32_e32 v2, v2
	v_rcp_f32_e32 v3, v3
	s_nop 0
	v_pk_mul_f32 v[0:1], v[2:3], v[0:1]
	s_nop 0
	v_pk_mul_f32 v[0:1], v[8:9], v[0:1]
	v_lshlrev_b32_e32 v2, 16, v35
	v_cvt_pk_bf16_f32 v0, v0, v1
	v_mul_f32_e32 v1, 0xbfb8aa3b, v2
	v_exp_f32_e32 v1, v1
	v_and_b32_e32 v3, 0xffff0000, v35
	v_add_f32_e32 v1, 1.0, v1
	v_rcp_f32_e32 v4, v1
	v_mul_f32_e32 v1, 0xbfb8aa3b, v3
	v_exp_f32_e32 v1, v1
	s_nop 0
	v_add_f32_e32 v1, 1.0, v1
	v_rcp_f32_e32 v5, v1
	s_nop 0
	v_pk_mul_f32 v[2:3], v[4:5], v[2:3]
	s_nop 0
	v_pk_mul_f32 v[2:3], v[10:11], v[2:3]
	s_nop 0
	v_cvt_pk_bf16_f32 v1, v2, v3
	global_store_dwordx2 v[16:17], v[0:1], off offset:96
	s_waitcnt vmcnt(7)
	v_lshlrev_b32_e32 v0, 16, v32
	v_and_b32_e32 v1, 0xffff0000, v32
	v_mul_f32_e32 v2, 0xbfb8aa3b, v0
	v_mul_f32_e32 v3, 0xbfb8aa3b, v1
	v_exp_f32_e32 v2, v2
	v_exp_f32_e32 v3, v3
	v_add_f32_e32 v2, 1.0, v2
	v_add_f32_e32 v3, 1.0, v3
	v_rcp_f32_e32 v2, v2
	v_rcp_f32_e32 v3, v3
	s_nop 0
	v_pk_mul_f32 v[0:1], v[2:3], v[0:1]
	s_nop 0
	v_pk_mul_f32 v[0:1], v[12:13], v[0:1]
	v_lshlrev_b32_e32 v2, 16, v33
	v_cvt_pk_bf16_f32 v0, v0, v1
	v_mul_f32_e32 v1, 0xbfb8aa3b, v2
	v_exp_f32_e32 v1, v1
	v_and_b32_e32 v3, 0xffff0000, v33
	v_add_f32_e32 v1, 1.0, v1
	v_rcp_f32_e32 v4, v1
	v_mul_f32_e32 v1, 0xbfb8aa3b, v3
	v_exp_f32_e32 v1, v1
	s_nop 0
	v_add_f32_e32 v1, 1.0, v1
	v_rcp_f32_e32 v5, v1
	s_nop 0
	v_pk_mul_f32 v[2:3], v[4:5], v[2:3]
	s_nop 0
	v_pk_mul_f32 v[2:3], v[14:15], v[2:3]
	s_nop 0
	v_cvt_pk_bf16_f32 v1, v2, v3
	global_store_dwordx2 v[16:17], v[0:1], off offset:112
	s_cmp_eq_u32 s11, 3
	s_cbranch_scc0 .LBB0_189
	s_bitcmp1_b32 s101, 1
	s_cbranch_scc1 .LBB0_174
	s_mov_b32 s101, 1
	s_mov_b64 s[2:3], -1
	s_branch .Ls3_pass2

.Ls3_attn:
	s_lshl_b32 s9, s20, 3
	s_branch .LBB0_293
